# k24: k16 + one static s_setprio 1 for waves 4-7 over the attention phase (reset to 0 at phase exit)
# baseline (speedup 1.0000x reference)
; #define GSYNC() xcd_barrier(xbar)
; __global__ void __launch_bounds__(512, 2) mega_fwd(Params p) {
;     ...
;         if (isA) {
;             prep_attn(p, j);
;             GSYNC();
;             for (int u = bx; u < 1024; u += G) {
;                 const int b = u >> 8, w = u & 255, xcd = w & 7, slot = w >> 3, h = 2 * xcd + (slot >> 4), qb = slot & 15, kvh = h >> 2;
;                 const bf16_t* rowb = proj + (size_t)(b * SEQ) * A_IN;
;                 att::attn_body(rowb + (size_t)(qb * 256) * A_IN + h * 128, rowb + 2048 + kvh * 128, rowb + 2560 + kvh * 128,
.LBB0_255:
	s_or_b64 exec, exec, s[36:37]
	v_readlane_b32 s14, v254, 7
	v_readlane_b32 s15, v254, 8
	s_andn2_b64 vcc, exec, s[14:15]
	s_waitcnt lgkmcnt(0)
	s_barrier
	s_cbranch_vccnz .LBB0_278
	s_lshl_b32 s72, s74, 7
	v_readlane_b32 s36, v253, 0
	s_lshl_b64 s[14:15], s[72:73], 2
	v_readlane_b32 s40, v253, 4
	v_readlane_b32 s50, v253, 14
	v_readlane_b32 s51, v253, 15
	v_readlane_b32 s41, v253, 5
	v_readlane_b32 s46, v253, 10
	v_readlane_b32 s47, v253, 11
	v_readlane_b32 s48, v253, 12
	v_readlane_b32 s49, v253, 13
	s_add_u32 s40, s40, s14
	v_readlane_b32 s24, v254, 5
	v_readlane_b32 s50, v254, 37
	v_mov_b32_e32 v238, 1
	s_addc_u32 s41, s41, s15
	v_readlane_b32 s46, v254, 40
	v_readlane_b32 s47, v253, 17
	s_mov_b32 s48, s2
	v_readlane_b32 s25, v254, 6
	v_readlane_b32 s51, v254, 38
	v_readlane_b32 s49, v254, 39
	s_movk_i32 s72, 0x2800
	v_readlane_b32 s37, v253, 1
	v_readlane_b32 s38, v253, 2
	v_readlane_b32 s39, v253, 3
	v_readlane_b32 s42, v253, 6
	v_readlane_b32 s43, v253, 7
	v_readlane_b32 s44, v253, 8
	v_readlane_b32 s45, v253, 9
	v_readfirstlane_b32 s20, v252
	s_nop 3
	s_cmp_lt_u32 s20, 0x100
	s_cbranch_scc1 .Lattn_prio_done
	s_setprio 1
.Lattn_prio_done:
	s_branch .LBB0_258

; __global__ void __launch_bounds__(512, 2) mega_fwd(Params p) {
;     ...
;                 __syncthreads();
;             }
;         } else {
.LBB0_277:
	s_setprio 0
	v_readlane_b32 s78, v254, 63
	v_readlane_b32 s80, v255, 1
	v_readlane_b32 s82, v255, 3
	v_readlane_b32 s84, v255, 5
	v_readlane_b32 s86, v255, 7
	v_readlane_b32 s20, v255, 9
	v_readlane_b32 s24, v255, 11
	v_readlane_b32 s44, v255, 13
	v_readlane_b32 s46, v255, 15
	v_readlane_b32 s48, v255, 17
	v_readlane_b32 s50, v255, 19
	v_readlane_b32 s79, v255, 0
	v_readlane_b32 s81, v255, 2
	v_readlane_b32 s83, v255, 4
	v_readlane_b32 s85, v255, 6
	v_readlane_b32 s87, v255, 8
	v_readlane_b32 s21, v255, 10
	v_readlane_b32 s25, v255, 12
	v_readlane_b32 s45, v255, 14
	v_readlane_b32 s47, v255, 16
	v_readlane_b32 s49, v255, 18
	v_readlane_b32 s51, v255, 20
	v_mov_b32_e32 v199, v238
